# P6 SwiGLU epilogue: packed bf16 rows moved between lanes (ds_bpermute) so 4 neighbouring lanes store 64 contiguous bytes; stores deferred one block to hide the LDS round trip
# baseline (speedup 1.0000x reference)
; __device__ __forceinline__ unsigned cvt_pk_bf16(float lo, float hi) { return pk2(lo, hi); }
;     __device__ __forceinline__ void operator()(const f32x4 (&acc)[2][2][4][2], const int upm, const int upn, const int usplit, int wr, int wc, int fr, int fq) const {
;         const int row0 = upm * BM + wr * 64 + fr, col = upn * 128 + wc * 32 + 8 * fq;
; #pragma unroll
;         for (int ai = 0; ai < 2; ++ai)
; #pragma unroll
;             for (int m = 0; m < 4; ++m) {
;                 const size_t row = (size_t)(row0 + ai * HALF + m * 16);
;                 float r[8];
; #pragma unroll
;                 for (int n = 0; n < 2; ++n)
; #pragma unroll
;                     for (int j = 0; j < 4; ++j) { const float gv = acc[ai][0][m][n][j], uv = acc[ai][1][m][n][j]; r[n * 4 + j] = gv * __builtin_amdgcn_rcpf(1.f + __expf(-gv)) * uv; }
;                 u32x4 o; o.x = cvt_pk_bf16(r[0], r[1]); o.y = cvt_pk_bf16(r[2], r[3]); o.z = cvt_pk_bf16(r[4], r[5]); o.w = cvt_pk_bf16(r[6], r[7]);
;                 *(u32x4*)(hid + row * FFH + col) = o;
;             }
.LBB0_1761:
	v_mul_f32_e32 v149, 0xbfb8aa3b, v132
	v_exp_f32_e32 v149, v149
	v_lshl_or_b32 v150, s0, 7, v146
	v_lshl_add_u32 v148, s56, 8, v144
	v_mbcnt_lo_u32_b32 v154, -1, 0
	v_mbcnt_hi_u32_b32 v154, -1, v154
	v_and_b32_e32 v155, 15, v154
	v_lshrrev_b32_e32 v156, 2, v154
	v_lshrrev_b32_e32 v157, 4, v154
	v_and_b32_e32 v158, 3, v154
	v_sub_u32_e32 v148, v148, v155
	v_add_u32_e32 v148, v148, v156
	v_sub_u32_e32 v159, v158, v157
	v_lshl_add_u32 v150, v159, 3, v150
	v_lshl_add_u32 v160, v158, 4, v156
	v_lshlrev_b32_e32 v160, 2, v160
	v_ashrrev_i32_e32 v151, 31, v150
	v_add_f32_e32 v149, 1.0, v149
	v_rcp_f32_e32 v152, v149
	v_mul_f32_e32 v149, 0xbfb8aa3b, v133
	v_exp_f32_e32 v149, v149
	s_and_b64 vcc, exec, s[40:41]
	s_mov_b32 s56, s44
	s_mov_b64 s[60:61], s[54:55]
	v_add_f32_e32 v149, 1.0, v149
	v_rcp_f32_e32 v153, v149
	s_mov_b64 s[58:59], s[48:49]
	v_pk_mul_f32 v[132:133], v[132:133], v[152:153]
	s_nop 0
	v_pk_mul_f32 v[128:129], v[128:129], v[132:133]
	v_mul_f32_e32 v132, 0xbfb8aa3b, v134
	v_mul_f32_e32 v133, 0xbfb8aa3b, v135
	v_exp_f32_e32 v132, v132
	v_exp_f32_e32 v133, v133
	v_add_f32_e32 v132, 1.0, v132
	v_add_f32_e32 v133, 1.0, v133
	v_rcp_f32_e32 v132, v132
	v_rcp_f32_e32 v133, v133
	s_nop 0
	v_pk_mul_f32 v[132:133], v[134:135], v[132:133]
	s_nop 0
	v_pk_mul_f32 v[130:131], v[130:131], v[132:133]
	v_mul_f32_e32 v132, 0xbfb8aa3b, v124
	v_mul_f32_e32 v133, 0xbfb8aa3b, v125
	v_exp_f32_e32 v132, v132
	v_exp_f32_e32 v133, v133
	v_add_f32_e32 v132, 1.0, v132
	v_add_f32_e32 v133, 1.0, v133
	v_rcp_f32_e32 v132, v132
	v_rcp_f32_e32 v133, v133
	s_nop 0
	v_pk_mul_f32 v[124:125], v[124:125], v[132:133]
	s_nop 0
	v_pk_mul_f32 v[120:121], v[120:121], v[124:125]
	v_mul_f32_e32 v124, 0xbfb8aa3b, v126
	v_mul_f32_e32 v125, 0xbfb8aa3b, v127
	v_exp_f32_e32 v124, v124
	v_exp_f32_e32 v125, v125
	v_add_f32_e32 v124, 1.0, v124
	v_add_f32_e32 v125, 1.0, v125
	v_rcp_f32_e32 v124, v124
	v_rcp_f32_e32 v125, v125
	s_nop 0
	v_pk_mul_f32 v[124:125], v[126:127], v[124:125]
	s_nop 0
	v_pk_mul_f32 v[122:123], v[122:123], v[124:125]
	v_cvt_pk_bf16_f32 v126, v120, v121
	v_mov_b64_e32 v[120:121], s[30:31]
	v_cvt_pk_bf16_f32 v124, v128, v129
	v_cvt_pk_bf16_f32 v127, v122, v123
	v_mad_i64_i32 v[128:129], s[0:1], v148, s9, v[120:121]
	v_lshlrev_b64 v[122:123], 1, v[150:151]
	v_cvt_pk_bf16_f32 v125, v130, v131
	v_lshl_add_u64 v[128:129], v[128:129], 0, v[122:123]
	ds_bpermute_b32 v162, v160, v124
	ds_bpermute_b32 v163, v160, v125
	ds_bpermute_b32 v164, v160, v126
	ds_bpermute_b32 v165, v160, v127
	v_mov_b32_e32 v166, v128
	v_mov_b32_e32 v167, v129
	s_nop 1
	v_mul_f32_e32 v124, 0xbfb8aa3b, v116
	v_mul_f32_e32 v125, 0xbfb8aa3b, v117
	v_exp_f32_e32 v124, v124
	v_exp_f32_e32 v125, v125
	v_or_b32_e32 v126, 16, v148
	v_add_f32_e32 v124, 1.0, v124
	v_add_f32_e32 v125, 1.0, v125
	v_rcp_f32_e32 v124, v124
	v_rcp_f32_e32 v125, v125
	s_nop 0
	v_pk_mul_f32 v[116:117], v[116:117], v[124:125]
	s_nop 0
	v_pk_mul_f32 v[112:113], v[112:113], v[116:117]
	v_mul_f32_e32 v116, 0xbfb8aa3b, v118
	v_mul_f32_e32 v117, 0xbfb8aa3b, v119
	v_exp_f32_e32 v116, v116
	v_exp_f32_e32 v117, v117
	v_add_f32_e32 v116, 1.0, v116
	v_add_f32_e32 v117, 1.0, v117
	v_rcp_f32_e32 v116, v116
	v_rcp_f32_e32 v117, v117
	s_nop 0
	v_pk_mul_f32 v[116:117], v[118:119], v[116:117]
	s_nop 0
	v_pk_mul_f32 v[114:115], v[114:115], v[116:117]
	v_mul_f32_e32 v116, 0xbfb8aa3b, v108
	v_mul_f32_e32 v117, 0xbfb8aa3b, v109
	v_exp_f32_e32 v116, v116
	v_exp_f32_e32 v117, v117
	v_add_f32_e32 v116, 1.0, v116
	v_add_f32_e32 v117, 1.0, v117
	v_rcp_f32_e32 v116, v116
	v_rcp_f32_e32 v117, v117
	s_nop 0
	v_pk_mul_f32 v[108:109], v[108:109], v[116:117]
	s_nop 0
	v_pk_mul_f32 v[108:109], v[104:105], v[108:109]
	v_mul_f32_e32 v104, 0xbfb8aa3b, v110
	v_mul_f32_e32 v105, 0xbfb8aa3b, v111
	v_exp_f32_e32 v104, v104
	v_exp_f32_e32 v105, v105
	v_add_f32_e32 v104, 1.0, v104
	v_add_f32_e32 v105, 1.0, v105
	v_rcp_f32_e32 v104, v104
	v_rcp_f32_e32 v105, v105
	s_nop 0
	v_pk_mul_f32 v[104:105], v[110:111], v[104:105]
	s_nop 0
	v_pk_mul_f32 v[110:111], v[106:107], v[104:105]
	v_cvt_pk_bf16_f32 v106, v108, v109
	v_mad_i64_i32 v[108:109], s[0:1], v126, s9, v[120:121]
	v_cvt_pk_bf16_f32 v104, v112, v113
	v_cvt_pk_bf16_f32 v105, v114, v115
	v_cvt_pk_bf16_f32 v107, v110, v111
	v_lshl_add_u64 v[108:109], v[108:109], 0, v[122:123]
	s_waitcnt lgkmcnt(0)
	global_store_dwordx4 v[166:167], v[162:165], off
	ds_bpermute_b32 v168, v160, v104
	ds_bpermute_b32 v169, v160, v105
	ds_bpermute_b32 v170, v160, v106
	ds_bpermute_b32 v171, v160, v107
	v_mov_b32_e32 v172, v108
	v_mov_b32_e32 v173, v109
	s_nop 1
	v_mul_f32_e32 v104, 0xbfb8aa3b, v100
	v_mul_f32_e32 v105, 0xbfb8aa3b, v101
	v_exp_f32_e32 v104, v104
	v_exp_f32_e32 v105, v105
	v_or_b32_e32 v106, 32, v148
	v_add_f32_e32 v104, 1.0, v104
	v_add_f32_e32 v105, 1.0, v105
	v_rcp_f32_e32 v104, v104
	v_rcp_f32_e32 v105, v105
	s_nop 0
	v_pk_mul_f32 v[100:101], v[100:101], v[104:105]
	s_nop 0
	v_pk_mul_f32 v[96:97], v[96:97], v[100:101]
	v_mul_f32_e32 v100, 0xbfb8aa3b, v102
	v_mul_f32_e32 v101, 0xbfb8aa3b, v103
	v_exp_f32_e32 v100, v100
	v_exp_f32_e32 v101, v101
	v_add_f32_e32 v100, 1.0, v100
	v_add_f32_e32 v101, 1.0, v101
	v_rcp_f32_e32 v100, v100
	v_rcp_f32_e32 v101, v101
	s_nop 0
	v_pk_mul_f32 v[100:101], v[102:103], v[100:101]
	s_nop 0
	v_pk_mul_f32 v[98:99], v[98:99], v[100:101]
	v_mul_f32_e32 v100, 0xbfb8aa3b, v92
	v_mul_f32_e32 v101, 0xbfb8aa3b, v93
	v_exp_f32_e32 v100, v100
	v_exp_f32_e32 v101, v101
	v_add_f32_e32 v100, 1.0, v100
	v_add_f32_e32 v101, 1.0, v101
	v_rcp_f32_e32 v100, v100
	v_rcp_f32_e32 v101, v101
	s_nop 0
	v_pk_mul_f32 v[92:93], v[92:93], v[100:101]
	s_nop 0
	v_pk_mul_f32 v[92:93], v[88:89], v[92:93]
	v_mul_f32_e32 v88, 0xbfb8aa3b, v94
	v_mul_f32_e32 v89, 0xbfb8aa3b, v95
	v_exp_f32_e32 v88, v88
	v_exp_f32_e32 v89, v89
	v_add_f32_e32 v88, 1.0, v88
	v_add_f32_e32 v89, 1.0, v89
	v_rcp_f32_e32 v88, v88
	v_rcp_f32_e32 v89, v89
	s_nop 0
	v_pk_mul_f32 v[88:89], v[94:95], v[88:89]
	s_nop 0
	v_pk_mul_f32 v[94:95], v[90:91], v[88:89]
	v_cvt_pk_bf16_f32 v90, v92, v93
	v_mad_i64_i32 v[92:93], s[0:1], v106, s9, v[120:121]
	v_cvt_pk_bf16_f32 v88, v96, v97
	v_cvt_pk_bf16_f32 v89, v98, v99
	v_cvt_pk_bf16_f32 v91, v94, v95
	v_lshl_add_u64 v[92:93], v[92:93], 0, v[122:123]
	s_waitcnt lgkmcnt(0)
; __device__ __forceinline__ unsigned cvt_pk_bf16(float lo, float hi) { return pk2(lo, hi); }
;     __device__ __forceinline__ void operator()(const f32x4 (&acc)[2][2][4][2], const int upm, const int upn, const int usplit, int wr, int wc, int fr, int fq) const {
;         const int row0 = upm * BM + wr * 64 + fr, col = upn * 128 + wc * 32 + 8 * fq;
; #pragma unroll
;         for (int ai = 0; ai < 2; ++ai)
; #pragma unroll
;             for (int m = 0; m < 4; ++m) {
;                 const size_t row = (size_t)(row0 + ai * HALF + m * 16);
;                 float r[8];
; #pragma unroll
;                 for (int n = 0; n < 2; ++n)
; #pragma unroll
;                     for (int j = 0; j < 4; ++j) { const float gv = acc[ai][0][m][n][j], uv = acc[ai][1][m][n][j]; r[n * 4 + j] = gv * __builtin_amdgcn_rcpf(1.f + __expf(-gv)) * uv; }
;                 u32x4 o; o.x = cvt_pk_bf16(r[0], r[1]); o.y = cvt_pk_bf16(r[2], r[3]); o.z = cvt_pk_bf16(r[4], r[5]); o.w = cvt_pk_bf16(r[6], r[7]);
;                 *(u32x4*)(hid + row * FFH + col) = o;
;             }
	global_store_dwordx4 v[172:173], v[168:171], off
	ds_bpermute_b32 v162, v160, v88
	ds_bpermute_b32 v163, v160, v89
	ds_bpermute_b32 v164, v160, v90
	ds_bpermute_b32 v165, v160, v91
	v_mov_b32_e32 v166, v92
	v_mov_b32_e32 v167, v93
	s_nop 1
	v_mul_f32_e32 v88, 0xbfb8aa3b, v84
	v_mul_f32_e32 v89, 0xbfb8aa3b, v85
	v_exp_f32_e32 v88, v88
	v_exp_f32_e32 v89, v89
	v_or_b32_e32 v90, 48, v148
	v_add_f32_e32 v88, 1.0, v88
	v_add_f32_e32 v89, 1.0, v89
	v_rcp_f32_e32 v88, v88
	v_rcp_f32_e32 v89, v89
	s_nop 0
	v_pk_mul_f32 v[84:85], v[84:85], v[88:89]
	s_nop 0
	v_pk_mul_f32 v[80:81], v[80:81], v[84:85]
	v_mul_f32_e32 v84, 0xbfb8aa3b, v86
	v_mul_f32_e32 v85, 0xbfb8aa3b, v87
	v_exp_f32_e32 v84, v84
	v_exp_f32_e32 v85, v85
	v_add_f32_e32 v84, 1.0, v84
	v_add_f32_e32 v85, 1.0, v85
	v_rcp_f32_e32 v84, v84
	v_rcp_f32_e32 v85, v85
	s_nop 0
	v_pk_mul_f32 v[84:85], v[86:87], v[84:85]
	s_nop 0
	v_pk_mul_f32 v[82:83], v[82:83], v[84:85]
	v_mul_f32_e32 v84, 0xbfb8aa3b, v76
	v_mul_f32_e32 v85, 0xbfb8aa3b, v77
	v_exp_f32_e32 v84, v84
	v_exp_f32_e32 v85, v85
	v_add_f32_e32 v84, 1.0, v84
	v_add_f32_e32 v85, 1.0, v85
	v_rcp_f32_e32 v84, v84
	v_rcp_f32_e32 v85, v85
	s_nop 0
	v_pk_mul_f32 v[76:77], v[76:77], v[84:85]
	s_nop 0
	v_pk_mul_f32 v[76:77], v[72:73], v[76:77]
	v_mul_f32_e32 v72, 0xbfb8aa3b, v78
	v_mul_f32_e32 v73, 0xbfb8aa3b, v79
	v_exp_f32_e32 v72, v72
	v_exp_f32_e32 v73, v73
	v_add_f32_e32 v72, 1.0, v72
	v_add_f32_e32 v73, 1.0, v73
	v_rcp_f32_e32 v72, v72
	v_rcp_f32_e32 v73, v73
	s_nop 0
	v_pk_mul_f32 v[72:73], v[78:79], v[72:73]
	s_nop 0
	v_pk_mul_f32 v[78:79], v[74:75], v[72:73]
	v_cvt_pk_bf16_f32 v74, v76, v77
	v_mad_i64_i32 v[76:77], s[0:1], v90, s9, v[120:121]
	v_cvt_pk_bf16_f32 v72, v80, v81
	v_cvt_pk_bf16_f32 v73, v82, v83
	v_cvt_pk_bf16_f32 v75, v78, v79
	v_lshl_add_u64 v[76:77], v[76:77], 0, v[122:123]
	s_waitcnt lgkmcnt(0)
	global_store_dwordx4 v[166:167], v[162:165], off
	ds_bpermute_b32 v168, v160, v72
	ds_bpermute_b32 v169, v160, v73
	ds_bpermute_b32 v170, v160, v74
	ds_bpermute_b32 v171, v160, v75
	v_mov_b32_e32 v172, v76
	v_mov_b32_e32 v173, v77
	s_nop 1
	v_mul_f32_e32 v72, 0xbfb8aa3b, v68
	v_mul_f32_e32 v73, 0xbfb8aa3b, v69
	v_exp_f32_e32 v72, v72
	v_exp_f32_e32 v73, v73
	v_add_u32_e32 v74, 0x80, v148
	v_add_f32_e32 v72, 1.0, v72
	v_add_f32_e32 v73, 1.0, v73
	v_rcp_f32_e32 v72, v72
	v_rcp_f32_e32 v73, v73
	s_nop 0
	v_pk_mul_f32 v[68:69], v[68:69], v[72:73]
	s_nop 0
	v_pk_mul_f32 v[64:65], v[64:65], v[68:69]
	v_mul_f32_e32 v68, 0xbfb8aa3b, v70
	v_mul_f32_e32 v69, 0xbfb8aa3b, v71
	v_exp_f32_e32 v68, v68
	v_exp_f32_e32 v69, v69
	v_add_f32_e32 v68, 1.0, v68
	v_add_f32_e32 v69, 1.0, v69
	v_rcp_f32_e32 v68, v68
	v_rcp_f32_e32 v69, v69
	s_nop 0
	v_pk_mul_f32 v[68:69], v[70:71], v[68:69]
	s_nop 0
	v_pk_mul_f32 v[66:67], v[66:67], v[68:69]
	v_mul_f32_e32 v68, 0xbfb8aa3b, v60
	v_mul_f32_e32 v69, 0xbfb8aa3b, v61
	v_exp_f32_e32 v68, v68
	v_exp_f32_e32 v69, v69
	v_add_f32_e32 v68, 1.0, v68
	v_add_f32_e32 v69, 1.0, v69
	v_rcp_f32_e32 v68, v68
	v_rcp_f32_e32 v69, v69
	s_nop 0
	v_pk_mul_f32 v[60:61], v[60:61], v[68:69]
	s_nop 0
	v_pk_mul_f32 v[60:61], v[56:57], v[60:61]
	v_mul_f32_e32 v56, 0xbfb8aa3b, v62
	v_mul_f32_e32 v57, 0xbfb8aa3b, v63
	v_exp_f32_e32 v56, v56
	v_exp_f32_e32 v57, v57
	v_add_f32_e32 v56, 1.0, v56
	v_add_f32_e32 v57, 1.0, v57
	v_rcp_f32_e32 v56, v56
	v_rcp_f32_e32 v57, v57
	s_nop 0
	v_pk_mul_f32 v[56:57], v[62:63], v[56:57]
	s_nop 0
	v_pk_mul_f32 v[62:63], v[58:59], v[56:57]
	v_cvt_pk_bf16_f32 v58, v60, v61
	v_mad_i64_i32 v[60:61], s[0:1], v74, s9, v[120:121]
	v_cvt_pk_bf16_f32 v56, v64, v65
	v_cvt_pk_bf16_f32 v57, v66, v67
	v_cvt_pk_bf16_f32 v59, v62, v63
	v_lshl_add_u64 v[60:61], v[60:61], 0, v[122:123]
	s_waitcnt lgkmcnt(0)
	global_store_dwordx4 v[172:173], v[168:171], off
	ds_bpermute_b32 v162, v160, v56
	ds_bpermute_b32 v163, v160, v57
	ds_bpermute_b32 v164, v160, v58
	ds_bpermute_b32 v165, v160, v59
	v_mov_b32_e32 v166, v60
	v_mov_b32_e32 v167, v61
	s_nop 1
	v_mul_f32_e32 v56, 0xbfb8aa3b, v52
	v_mul_f32_e32 v57, 0xbfb8aa3b, v53
	v_exp_f32_e32 v56, v56
	v_exp_f32_e32 v57, v57
	v_add_u32_e32 v58, 0x90, v148
	v_add_f32_e32 v56, 1.0, v56
	v_add_f32_e32 v57, 1.0, v57
	v_rcp_f32_e32 v56, v56
	v_rcp_f32_e32 v57, v57
	s_nop 0
	v_pk_mul_f32 v[52:53], v[52:53], v[56:57]
	s_nop 0
	v_pk_mul_f32 v[48:49], v[48:49], v[52:53]
	v_mul_f32_e32 v52, 0xbfb8aa3b, v54
	v_mul_f32_e32 v53, 0xbfb8aa3b, v55
	v_exp_f32_e32 v52, v52
	v_exp_f32_e32 v53, v53
	v_add_f32_e32 v52, 1.0, v52
	v_add_f32_e32 v53, 1.0, v53
	v_rcp_f32_e32 v52, v52
	v_rcp_f32_e32 v53, v53
	s_nop 0
	v_pk_mul_f32 v[52:53], v[54:55], v[52:53]
	s_nop 0
	v_pk_mul_f32 v[50:51], v[50:51], v[52:53]
	v_mul_f32_e32 v52, 0xbfb8aa3b, v44
	v_mul_f32_e32 v53, 0xbfb8aa3b, v45
	v_exp_f32_e32 v52, v52
	v_exp_f32_e32 v53, v53
	v_add_f32_e32 v52, 1.0, v52
	v_add_f32_e32 v53, 1.0, v53
	v_rcp_f32_e32 v52, v52
	v_rcp_f32_e32 v53, v53
	s_nop 0
	v_pk_mul_f32 v[44:45], v[44:45], v[52:53]
	s_nop 0
	v_pk_mul_f32 v[44:45], v[40:41], v[44:45]
	v_mul_f32_e32 v40, 0xbfb8aa3b, v46
	v_mul_f32_e32 v41, 0xbfb8aa3b, v47
	v_exp_f32_e32 v40, v40
	v_exp_f32_e32 v41, v41
	v_add_f32_e32 v40, 1.0, v40
	v_add_f32_e32 v41, 1.0, v41
	v_rcp_f32_e32 v40, v40
	v_rcp_f32_e32 v41, v41
	s_nop 0
	v_pk_mul_f32 v[40:41], v[46:47], v[40:41]
	s_nop 0
	v_pk_mul_f32 v[46:47], v[42:43], v[40:41]
	v_cvt_pk_bf16_f32 v42, v44, v45
	v_mad_i64_i32 v[44:45], s[0:1], v58, s9, v[120:121]
	v_cvt_pk_bf16_f32 v40, v48, v49
	v_cvt_pk_bf16_f32 v41, v50, v51
	v_cvt_pk_bf16_f32 v43, v46, v47
	v_lshl_add_u64 v[44:45], v[44:45], 0, v[122:123]
	s_waitcnt lgkmcnt(0)
; __device__ __forceinline__ unsigned cvt_pk_bf16(float lo, float hi) { return pk2(lo, hi); }
;     __device__ __forceinline__ void operator()(const f32x4 (&acc)[2][2][4][2], const int upm, const int upn, const int usplit, int wr, int wc, int fr, int fq) const {
;         const int row0 = upm * BM + wr * 64 + fr, col = upn * 128 + wc * 32 + 8 * fq;
; #pragma unroll
;         for (int ai = 0; ai < 2; ++ai)
; #pragma unroll
;             for (int m = 0; m < 4; ++m) {
;                 const size_t row = (size_t)(row0 + ai * HALF + m * 16);
;                 float r[8];
; #pragma unroll
;                 for (int n = 0; n < 2; ++n)
; #pragma unroll
;                     for (int j = 0; j < 4; ++j) { const float gv = acc[ai][0][m][n][j], uv = acc[ai][1][m][n][j]; r[n * 4 + j] = gv * __builtin_amdgcn_rcpf(1.f + __expf(-gv)) * uv; }
;                 u32x4 o; o.x = cvt_pk_bf16(r[0], r[1]); o.y = cvt_pk_bf16(r[2], r[3]); o.z = cvt_pk_bf16(r[4], r[5]); o.w = cvt_pk_bf16(r[6], r[7]);
;                 *(u32x4*)(hid + row * FFH + col) = o;
;             }
	global_store_dwordx4 v[166:167], v[162:165], off
	ds_bpermute_b32 v168, v160, v40
	ds_bpermute_b32 v169, v160, v41
	ds_bpermute_b32 v170, v160, v42
	ds_bpermute_b32 v171, v160, v43
	v_mov_b32_e32 v172, v44
	v_mov_b32_e32 v173, v45
	s_nop 1
	v_mul_f32_e32 v40, 0xbfb8aa3b, v36
	v_mul_f32_e32 v41, 0xbfb8aa3b, v37
	v_exp_f32_e32 v40, v40
	v_exp_f32_e32 v41, v41
	v_add_u32_e32 v42, 0xa0, v148
	v_add_f32_e32 v40, 1.0, v40
	v_add_f32_e32 v41, 1.0, v41
	v_rcp_f32_e32 v40, v40
	v_rcp_f32_e32 v41, v41
	s_nop 0
	v_pk_mul_f32 v[36:37], v[36:37], v[40:41]
	s_nop 0
	v_pk_mul_f32 v[32:33], v[32:33], v[36:37]
	v_mul_f32_e32 v36, 0xbfb8aa3b, v38
	v_mul_f32_e32 v37, 0xbfb8aa3b, v39
	v_exp_f32_e32 v36, v36
	v_exp_f32_e32 v37, v37
	v_add_f32_e32 v36, 1.0, v36
	v_add_f32_e32 v37, 1.0, v37
	v_rcp_f32_e32 v36, v36
	v_rcp_f32_e32 v37, v37
	s_nop 0
	v_pk_mul_f32 v[36:37], v[38:39], v[36:37]
	s_nop 0
	v_pk_mul_f32 v[34:35], v[34:35], v[36:37]
	v_mul_f32_e32 v36, 0xbfb8aa3b, v28
	v_mul_f32_e32 v37, 0xbfb8aa3b, v29
	v_exp_f32_e32 v36, v36
	v_exp_f32_e32 v37, v37
	v_add_f32_e32 v36, 1.0, v36
	v_add_f32_e32 v37, 1.0, v37
	v_rcp_f32_e32 v36, v36
	v_rcp_f32_e32 v37, v37
	s_nop 0
	v_pk_mul_f32 v[28:29], v[28:29], v[36:37]
	s_nop 0
	v_pk_mul_f32 v[28:29], v[24:25], v[28:29]
	v_mul_f32_e32 v24, 0xbfb8aa3b, v30
	v_mul_f32_e32 v25, 0xbfb8aa3b, v31
	v_exp_f32_e32 v24, v24
	v_exp_f32_e32 v25, v25
	v_add_f32_e32 v24, 1.0, v24
	v_add_f32_e32 v25, 1.0, v25
	v_rcp_f32_e32 v24, v24
	v_rcp_f32_e32 v25, v25
	s_nop 0
	v_pk_mul_f32 v[24:25], v[30:31], v[24:25]
	s_nop 0
	v_pk_mul_f32 v[30:31], v[26:27], v[24:25]
	v_cvt_pk_bf16_f32 v26, v28, v29
	v_mad_i64_i32 v[28:29], s[0:1], v42, s9, v[120:121]
	v_cvt_pk_bf16_f32 v24, v32, v33
	v_cvt_pk_bf16_f32 v25, v34, v35
	v_cvt_pk_bf16_f32 v27, v30, v31
	v_lshl_add_u64 v[28:29], v[28:29], 0, v[122:123]
	s_waitcnt lgkmcnt(0)
	global_store_dwordx4 v[172:173], v[168:171], off
	ds_bpermute_b32 v162, v160, v24
	ds_bpermute_b32 v163, v160, v25
	ds_bpermute_b32 v164, v160, v26
	ds_bpermute_b32 v165, v160, v27
	v_mov_b32_e32 v166, v28
	v_mov_b32_e32 v167, v29
	s_nop 1
	v_mul_f32_e32 v24, 0xbfb8aa3b, v20
	v_mul_f32_e32 v25, 0xbfb8aa3b, v21
	v_exp_f32_e32 v24, v24
	v_exp_f32_e32 v25, v25
	v_add_u32_e32 v26, 0xb0, v148
	v_add_f32_e32 v24, 1.0, v24
	v_add_f32_e32 v25, 1.0, v25
	v_rcp_f32_e32 v24, v24
	v_rcp_f32_e32 v25, v25
	s_nop 0
	v_pk_mul_f32 v[20:21], v[20:21], v[24:25]
	s_nop 0
	v_pk_mul_f32 v[16:17], v[16:17], v[20:21]
	v_mul_f32_e32 v20, 0xbfb8aa3b, v22
	v_mul_f32_e32 v21, 0xbfb8aa3b, v23
	v_exp_f32_e32 v20, v20
	v_exp_f32_e32 v21, v21
	v_add_f32_e32 v20, 1.0, v20
	v_add_f32_e32 v21, 1.0, v21
	v_rcp_f32_e32 v20, v20
	v_rcp_f32_e32 v21, v21
	s_nop 0
	v_pk_mul_f32 v[20:21], v[22:23], v[20:21]
	s_nop 0
	v_pk_mul_f32 v[18:19], v[18:19], v[20:21]
	v_mul_f32_e32 v20, 0xbfb8aa3b, v12
	v_mul_f32_e32 v21, 0xbfb8aa3b, v13
	v_exp_f32_e32 v20, v20
	v_exp_f32_e32 v21, v21
	v_add_f32_e32 v20, 1.0, v20
	v_add_f32_e32 v21, 1.0, v21
	v_rcp_f32_e32 v20, v20
	v_rcp_f32_e32 v21, v21
	s_nop 0
	v_pk_mul_f32 v[12:13], v[12:13], v[20:21]
	s_nop 0
	v_pk_mul_f32 v[12:13], v[8:9], v[12:13]
	v_mul_f32_e32 v8, 0xbfb8aa3b, v14
	v_mul_f32_e32 v9, 0xbfb8aa3b, v15
	v_exp_f32_e32 v8, v8
	v_exp_f32_e32 v9, v9
	v_add_f32_e32 v8, 1.0, v8
	v_add_f32_e32 v9, 1.0, v9
	v_rcp_f32_e32 v8, v8
	v_rcp_f32_e32 v9, v9
	s_nop 0
	v_pk_mul_f32 v[8:9], v[14:15], v[8:9]
	s_nop 0
	v_pk_mul_f32 v[14:15], v[10:11], v[8:9]
	v_cvt_pk_bf16_f32 v10, v12, v13
	v_mad_i64_i32 v[12:13], s[0:1], v26, s9, v[120:121]
	v_cvt_pk_bf16_f32 v8, v16, v17
	v_cvt_pk_bf16_f32 v9, v18, v19
	v_cvt_pk_bf16_f32 v11, v14, v15
	v_lshl_add_u64 v[12:13], v[12:13], 0, v[122:123]
	s_mov_b32 s0, s46
	s_mov_b32 s1, s20
	s_waitcnt lgkmcnt(0)
	global_store_dwordx4 v[166:167], v[162:165], off
	ds_bpermute_b32 v168, v160, v8
	ds_bpermute_b32 v169, v160, v9
	ds_bpermute_b32 v170, v160, v10
	ds_bpermute_b32 v171, v160, v11
	v_mov_b32_e32 v172, v12
	v_mov_b32_e32 v173, v13
	s_waitcnt lgkmcnt(0)
	global_store_dwordx4 v[172:173], v[168:171], off
	s_cbranch_vccnz .LBB0_1767
